# flash loops: row-max cross-half exchange via v_permlane32_swap on two copies instead of ds_bpermute + lgkmcnt wait
# baseline (speedup 1.0000x reference)
;     ...
;   float mx = fmaxf(S[0][0], S[0][1]);
; #pragma unroll
;   for (int ks = 0; ks < 2; ++ks)
; #pragma unroll
;     for (int i = (ks ? 0 : 2); i < 16; i += 2) mx = fmaxf(fmaxf(mx, S[ks][i]), S[ks][i + 1]);
;   mx = fmaxf(mx, __shfl_xor(mx, 32));
;   if (MODE == 2) mx = selbit ? mx : -1e30f;
;   const float mn = fmaxf(m, mx);
;   if (__any((mn - m) * c2 > 8.f)) {
;     const float alpha = __builtin_amdgcn_exp2f((m - mn) * c2);
;     m = mn;
;     l *= alpha;
; #pragma unroll
;     for (int d = 0; d < DV / 32; ++d) O[d] = O[d] * alpha;
;   }
.LBB0_360:
	s_or_b64 exec, exec, s[12:13]
	v_max_f32_e32 v104, v51, v51
	v_max_f32_e32 v117, v50, v50
	v_max_f32_e32 v104, v117, v104
	v_max3_f32 v104, v104, v52, v53
	v_max3_f32 v104, v104, v54, v55
	v_max3_f32 v104, v104, v56, v57
	v_max3_f32 v104, v104, v58, v59
	v_max3_f32 v104, v104, v60, v61
	v_max3_f32 v104, v104, v62, v63
	v_max3_f32 v104, v104, v64, v65
	v_max3_f32 v104, v104, v34, v35
	v_max3_f32 v104, v104, v36, v37
	v_max3_f32 v104, v104, v38, v39
	v_max3_f32 v104, v104, v40, v41
	v_and_b32_e32 v118, 64, v207
	v_max3_f32 v104, v104, v42, v43
	v_xor_b32_e32 v117, 32, v207
	v_add_u32_e32 v118, 64, v118
	v_max3_f32 v104, v104, v44, v45
	v_cmp_lt_i32_e32 vcc, v117, v118
	v_max3_f32 v104, v104, v46, v47
	v_max3_f32 v104, v104, v48, v49
	v_cndmask_b32_e32 v117, v207, v117, vcc
	v_lshlrev_b32_e32 v117, 2, v117
	v_mov_b32_e32 v118, v104
	v_mov_b32_e32 v119, v104
	s_nop 1
	v_permlane32_swap_b32_e32 v118, v119
	ds_read2_b64 v[216:219], v131 offset0:128 offset1:130
	ds_read2_b64 v[220:223], v130 offset0:192 offset1:194
	ds_read2_b64 v[224:227], v131 offset0:132 offset1:134
	ds_read2_b64 v[228:231], v130 offset0:196 offset1:198
	ds_read2_b64 v[232:235], v131 offset0:136 offset1:138
	ds_read2_b64 v[236:239], v130 offset0:200 offset1:202
	ds_read2_b64 v[240:243], v131 offset0:140 offset1:142
	ds_read2_b64 v[244:247], v130 offset0:204 offset1:206
	v_max3_f32 v104, v116, v118, v119
	v_sub_f32_e32 v118, v104, v116
	v_mul_f32_e32 v118, 0x3e16c740, v118
	v_cmp_lt_f32_e32 vcc, s51, v118
	s_cbranch_vccz .LBB0_377
	v_sub_f32_e32 v116, v116, v104
	v_mul_f32_e32 v116, 0x3e16c740, v116
	v_exp_f32_e32 v116, v116
	s_nop 0
	v_mul_f32_e32 v109, v109, v116
	v_pk_mul_f32 v[16:17], v[16:17], v[116:117] op_sel_hi:[1,0]
	v_pk_mul_f32 v[14:15], v[14:15], v[116:117] op_sel_hi:[1,0]
	v_pk_mul_f32 v[12:13], v[12:13], v[116:117] op_sel_hi:[1,0]
	v_pk_mul_f32 v[10:11], v[10:11], v[116:117] op_sel_hi:[1,0]
	v_pk_mul_f32 v[8:9], v[8:9], v[116:117] op_sel_hi:[1,0]
	v_pk_mul_f32 v[6:7], v[6:7], v[116:117] op_sel_hi:[1,0]
	v_pk_mul_f32 v[4:5], v[4:5], v[116:117] op_sel_hi:[1,0]
	v_pk_mul_f32 v[2:3], v[2:3], v[116:117] op_sel_hi:[1,0]
	v_pk_mul_f32 v[32:33], v[32:33], v[116:117] op_sel_hi:[1,0]
	v_pk_mul_f32 v[30:31], v[30:31], v[116:117] op_sel_hi:[1,0]
	v_pk_mul_f32 v[28:29], v[28:29], v[116:117] op_sel_hi:[1,0]
	v_pk_mul_f32 v[26:27], v[26:27], v[116:117] op_sel_hi:[1,0]
	v_pk_mul_f32 v[24:25], v[24:25], v[116:117] op_sel_hi:[1,0]
	v_pk_mul_f32 v[22:23], v[22:23], v[116:117] op_sel_hi:[1,0]
	v_pk_mul_f32 v[20:21], v[20:21], v[116:117] op_sel_hi:[1,0]
	v_pk_mul_f32 v[18:19], v[18:19], v[116:117] op_sel_hi:[1,0]
	v_mov_b32_e32 v116, v104

;     ...
;   float mx = fmaxf(S[0][0], S[0][1]);
; #pragma unroll
;   for (int ks = 0; ks < 2; ++ks)
; #pragma unroll
;     for (int i = (ks ? 0 : 2); i < 16; i += 2) mx = fmaxf(fmaxf(mx, S[ks][i]), S[ks][i + 1]);
;   mx = fmaxf(mx, __shfl_xor(mx, 32));
;   if (MODE == 2) mx = selbit ? mx : -1e30f;
;   const float mn = fmaxf(m, mx);
;   if (__any((mn - m) * c2 > 8.f)) {
.LBB0_439:
	s_nop 0
	v_max_f32_e32 v110, v83, v83
	v_max_f32_e32 v119, v82, v82
	v_max_f32_e32 v110, v119, v110
	v_max3_f32 v110, v110, v84, v85
	v_max3_f32 v110, v110, v86, v87
	v_max3_f32 v110, v110, v88, v89
	v_max3_f32 v110, v110, v90, v91
	v_max3_f32 v110, v110, v92, v93
	v_max3_f32 v110, v110, v94, v95
	v_max3_f32 v110, v110, v96, v97
	v_max3_f32 v110, v110, v66, v67
	v_max3_f32 v110, v110, v68, v69
	v_max3_f32 v110, v110, v70, v71
	v_max3_f32 v110, v110, v72, v73
	v_max3_f32 v110, v110, v74, v75
	v_max3_f32 v110, v110, v76, v77
	v_max3_f32 v110, v110, v78, v79
	v_max3_f32 v110, v110, v80, v81
	v_mov_b32_e32 v119, v110
	v_mov_b32_e32 v120, v110
	s_nop 1
	v_permlane32_swap_b32_e32 v119, v120
	ds_read2_b64 v[216:219], v243 offset0:128 offset1:130
	ds_read2_b64 v[220:223], v247 offset0:192 offset1:194
	ds_read2_b64 v[224:227], v243 offset0:132 offset1:134
	ds_read2_b64 v[228:231], v247 offset0:196 offset1:198
	ds_read2_b64 v[232:235], v243 offset0:136 offset1:138
	ds_read2_b64 v[236:239], v247 offset0:200 offset1:202
	ds_read2_b64 v[240:243], v243 offset0:140 offset1:142
	ds_read2_b64 v[244:247], v247 offset0:204 offset1:206
	v_max_f32_e32 v119, v119, v120
	v_max_f32_e32 v110, v110, v119
	v_cndmask_b32_e64 v110, v208, v110, s[10:11]
	v_max_f32_e32 v119, v118, v118
	v_max_f32_e32 v110, v119, v110
	v_sub_f32_e32 v119, v110, v118
	v_mul_f32_e32 v119, 0x3e38aa3b, v119
	v_cmp_lt_f32_e32 vcc, s51, v119
	s_cbranch_vccnz .LBB0_423
	v_mov_b32_e32 v110, v118
	s_branch .LBB0_424

;     ...
;   float mx = fmaxf(S[0][0], S[0][1]);
; #pragma unroll
;   for (int ks = 0; ks < 2; ++ks)
; #pragma unroll
;     for (int i = (ks ? 0 : 2); i < 16; i += 2) mx = fmaxf(fmaxf(mx, S[ks][i]), S[ks][i + 1]);
;   mx = fmaxf(mx, __shfl_xor(mx, 32));
;   if (MODE == 2) mx = selbit ? mx : -1e30f;
;   const float mn = fmaxf(m, mx);
;   if (__any((mn - m) * c2 > 8.f)) {
;     const float alpha = __builtin_amdgcn_exp2f((m - mn) * c2);
;     m = mn;
;     l *= alpha;
; #pragma unroll
;     for (int d = 0; d < DV / 32; ++d) O[d] = O[d] * alpha;
;   }
.LBB0_470:
	s_nop 0
	v_max_f32_e32 v162, v115, v115
	v_max_f32_e32 v179, v114, v114
	v_max_f32_e32 v162, v179, v162
	v_max3_f32 v162, v162, v116, v117
	v_max3_f32 v162, v162, v118, v119
	v_max3_f32 v162, v162, v120, v121
	v_max3_f32 v162, v162, v122, v123
	v_max3_f32 v162, v162, v124, v125
	v_max3_f32 v162, v162, v126, v127
	v_max3_f32 v162, v162, v128, v129
	v_max3_f32 v162, v162, v98, v99
	v_max3_f32 v162, v162, v100, v101
	v_max3_f32 v162, v162, v102, v103
	v_max3_f32 v162, v162, v104, v105
	v_max3_f32 v162, v162, v106, v107
	v_max3_f32 v162, v162, v108, v109
	v_max3_f32 v162, v162, v110, v111
	v_max3_f32 v162, v162, v112, v113
	v_mov_b32_e32 v179, v162
	v_mov_b32_e32 v180, v162
	s_nop 1
	v_permlane32_swap_b32_e32 v179, v180
	ds_read2_b64 v[216:219], v243 offset0:128 offset1:130
	ds_read2_b64 v[220:223], v247 offset0:192 offset1:194
	ds_read2_b64 v[224:227], v243 offset0:132 offset1:134
	ds_read2_b64 v[228:231], v247 offset0:196 offset1:198
	ds_read2_b64 v[232:235], v243 offset0:136 offset1:138
	ds_read2_b64 v[236:239], v247 offset0:200 offset1:202
	ds_read2_b64 v[240:243], v243 offset0:140 offset1:142
	ds_read2_b64 v[244:247], v247 offset0:204 offset1:206
	v_max3_f32 v162, v178, v179, v180
	v_sub_f32_e32 v179, v162, v178
	v_mul_f32_e32 v179, 0x3e38aa3b, v179
	v_cmp_lt_f32_e32 vcc, s51, v179
	s_cbranch_vccnz .LBB0_454
	v_mov_b32_e32 v162, v178
	s_branch .LBB0_455

;     ...
;   float mx = fmaxf(S[0][0], S[0][1]);
; #pragma unroll
;   for (int ks = 0; ks < 2; ++ks)
; #pragma unroll
;     for (int i = (ks ? 0 : 2); i < 16; i += 2) mx = fmaxf(fmaxf(mx, S[ks][i]), S[ks][i + 1]);
;   mx = fmaxf(mx, __shfl_xor(mx, 32));
;   if (MODE == 2) mx = selbit ? mx : -1e30f;
;   const float mn = fmaxf(m, mx);
;   if (__any((mn - m) * c2 > 8.f)) {
;     const float alpha = __builtin_amdgcn_exp2f((m - mn) * c2);
;     m = mn;
;     l *= alpha;
; #pragma unroll
;     for (int d = 0; d < DV / 32; ++d) O[d] = O[d] * alpha;
;   }
.LBB0_485:
	s_or_b64 exec, exec, s[12:13]
	v_max_f32_e32 v104, v51, v51
	v_max_f32_e32 v117, v50, v50
	v_max_f32_e32 v104, v117, v104
	v_max3_f32 v104, v104, v52, v53
	v_max3_f32 v104, v104, v54, v55
	v_max3_f32 v104, v104, v56, v57
	v_max3_f32 v104, v104, v58, v59
	v_max3_f32 v104, v104, v60, v61
	v_max3_f32 v104, v104, v62, v63
	v_max3_f32 v104, v104, v64, v65
	v_max3_f32 v104, v104, v34, v35
	v_max3_f32 v104, v104, v36, v37
	v_max3_f32 v104, v104, v38, v39
	v_max3_f32 v104, v104, v40, v41
	v_max3_f32 v104, v104, v42, v43
	v_max3_f32 v104, v104, v44, v45
	v_max3_f32 v104, v104, v46, v47
	v_max3_f32 v104, v104, v48, v49
	v_mov_b32_e32 v117, v104
	v_mov_b32_e32 v118, v104
	s_nop 1
	v_permlane32_swap_b32_e32 v117, v118
	ds_read2_b64 v[216:219], v131 offset0:128 offset1:130
	ds_read2_b64 v[220:223], v130 offset0:192 offset1:194
	ds_read2_b64 v[224:227], v131 offset0:132 offset1:134
	ds_read2_b64 v[228:231], v130 offset0:196 offset1:198
	ds_read2_b64 v[232:235], v131 offset0:136 offset1:138
	ds_read2_b64 v[236:239], v130 offset0:200 offset1:202
	ds_read2_b64 v[240:243], v131 offset0:140 offset1:142
	ds_read2_b64 v[244:247], v130 offset0:204 offset1:206
	v_max3_f32 v104, v116, v117, v118
	v_sub_f32_e32 v117, v104, v116
	v_mul_f32_e32 v117, 0x3e16c740, v117
	v_cmp_lt_f32_e32 vcc, s51, v117
	s_cbranch_vccz .LBB0_502
	v_sub_f32_e32 v116, v116, v104
	v_mul_f32_e32 v116, 0x3e16c740, v116
	v_exp_f32_e32 v116, v116
	s_nop 0
	v_mul_f32_e32 v109, v109, v116
	v_pk_mul_f32 v[16:17], v[16:17], v[116:117] op_sel_hi:[1,0]
	v_pk_mul_f32 v[14:15], v[14:15], v[116:117] op_sel_hi:[1,0]
	v_pk_mul_f32 v[12:13], v[12:13], v[116:117] op_sel_hi:[1,0]
	v_pk_mul_f32 v[10:11], v[10:11], v[116:117] op_sel_hi:[1,0]
	v_pk_mul_f32 v[8:9], v[8:9], v[116:117] op_sel_hi:[1,0]
	v_pk_mul_f32 v[6:7], v[6:7], v[116:117] op_sel_hi:[1,0]
	v_pk_mul_f32 v[4:5], v[4:5], v[116:117] op_sel_hi:[1,0]
	v_pk_mul_f32 v[2:3], v[2:3], v[116:117] op_sel_hi:[1,0]
	v_pk_mul_f32 v[32:33], v[32:33], v[116:117] op_sel_hi:[1,0]
	v_pk_mul_f32 v[30:31], v[30:31], v[116:117] op_sel_hi:[1,0]
	v_pk_mul_f32 v[28:29], v[28:29], v[116:117] op_sel_hi:[1,0]
	v_pk_mul_f32 v[26:27], v[26:27], v[116:117] op_sel_hi:[1,0]
	v_pk_mul_f32 v[24:25], v[24:25], v[116:117] op_sel_hi:[1,0]
	v_pk_mul_f32 v[22:23], v[22:23], v[116:117] op_sel_hi:[1,0]
	v_pk_mul_f32 v[20:21], v[20:21], v[116:117] op_sel_hi:[1,0]
	v_pk_mul_f32 v[18:19], v[18:19], v[116:117] op_sel_hi:[1,0]
	v_mov_b32_e32 v116, v104

;     ...
;   float mx = fmaxf(S[0][0], S[0][1]);
; #pragma unroll
;   for (int ks = 0; ks < 2; ++ks)
; #pragma unroll
;     for (int i = (ks ? 0 : 2); i < 16; i += 2) mx = fmaxf(fmaxf(mx, S[ks][i]), S[ks][i + 1]);
;   mx = fmaxf(mx, __shfl_xor(mx, 32));
;   if (MODE == 2) mx = selbit ? mx : -1e30f;
;   const float mn = fmaxf(m, mx);
;   if (__any((mn - m) * c2 > 8.f)) {
.LBB0_564:
	s_nop 0
	v_max_f32_e32 v14, v97, v97
	v_max_f32_e32 v119, v96, v96
	v_max_f32_e32 v14, v119, v14
	v_max3_f32 v14, v14, v98, v99
	v_max3_f32 v14, v14, v100, v101
	v_max3_f32 v14, v14, v102, v103
	v_max3_f32 v14, v14, v104, v105
	v_max3_f32 v14, v14, v106, v107
	v_max3_f32 v14, v14, v108, v109
	v_max3_f32 v14, v14, v110, v111
	v_max3_f32 v14, v14, v80, v81
	v_max3_f32 v14, v14, v82, v83
	v_max3_f32 v14, v14, v84, v85
	v_max3_f32 v14, v14, v86, v87
	v_max3_f32 v14, v14, v88, v89
	v_max3_f32 v14, v14, v90, v91
	v_max3_f32 v14, v14, v92, v93
	v_max3_f32 v14, v14, v94, v95
	v_mov_b32_e32 v119, v14
	v_mov_b32_e32 v120, v14
	s_nop 1
	v_permlane32_swap_b32_e32 v119, v120
	ds_read2_b64 v[216:219], v243 offset0:128 offset1:130
	ds_read2_b64 v[220:223], v247 offset0:192 offset1:194
	ds_read2_b64 v[224:227], v243 offset0:132 offset1:134
	ds_read2_b64 v[228:231], v247 offset0:196 offset1:198
	ds_read2_b64 v[232:235], v243 offset0:136 offset1:138
	ds_read2_b64 v[236:239], v247 offset0:200 offset1:202
	ds_read2_b64 v[240:243], v243 offset0:140 offset1:142
	ds_read2_b64 v[244:247], v247 offset0:204 offset1:206
	v_max_f32_e32 v119, v119, v120
	v_max_f32_e32 v14, v14, v119
	v_cndmask_b32_e64 v14, v208, v14, s[10:11]
	v_max_f32_e32 v119, v118, v118
	v_max_f32_e32 v14, v119, v14
	v_sub_f32_e32 v119, v14, v118
	v_mul_f32_e32 v119, 0x3e38aa3b, v119
	v_cmp_lt_f32_e32 vcc, s51, v119
	s_cbranch_vccnz .LBB0_548
	v_mov_b32_e32 v14, v118
	s_branch .LBB0_549

;     ...
;   float mx = fmaxf(S[0][0], S[0][1]);
; #pragma unroll
;   for (int ks = 0; ks < 2; ++ks)
; #pragma unroll
;     for (int i = (ks ? 0 : 2); i < 16; i += 2) mx = fmaxf(fmaxf(mx, S[ks][i]), S[ks][i + 1]);
;   mx = fmaxf(mx, __shfl_xor(mx, 32));
;   if (MODE == 2) mx = selbit ? mx : -1e30f;
;   const float mn = fmaxf(m, mx);
;   if (__any((mn - m) * c2 > 8.f)) {
;     const float alpha = __builtin_amdgcn_exp2f((m - mn) * c2);
;     m = mn;
;     l *= alpha;
; #pragma unroll
;     for (int d = 0; d < DV / 32; ++d) O[d] = O[d] * alpha;
;   }
.LBB0_600:
	s_nop 0
	v_max_f32_e32 v12, v129, v129
	v_max_f32_e32 v176, v128, v128
	v_max_f32_e32 v12, v176, v12
	v_max3_f32 v12, v12, v130, v131
	v_max3_f32 v12, v12, v132, v133
	v_max3_f32 v12, v12, v134, v135
	v_max3_f32 v12, v12, v136, v137
	v_max3_f32 v12, v12, v138, v139
	v_max3_f32 v12, v12, v140, v141
	v_max3_f32 v12, v12, v142, v143
	v_max3_f32 v12, v12, v112, v113
	v_max3_f32 v12, v12, v114, v115
	v_max3_f32 v12, v12, v116, v117
	v_max3_f32 v12, v12, v118, v119
	v_max3_f32 v12, v12, v120, v121
	v_max3_f32 v12, v12, v122, v123
	v_max3_f32 v12, v12, v124, v125
	v_max3_f32 v12, v12, v126, v127
	v_mov_b32_e32 v176, v12
	v_mov_b32_e32 v177, v12
	s_nop 1
	v_permlane32_swap_b32_e32 v176, v177
	ds_read2_b64 v[216:219], v243 offset0:128 offset1:130
	ds_read2_b64 v[220:223], v247 offset0:192 offset1:194
	ds_read2_b64 v[224:227], v243 offset0:132 offset1:134
	ds_read2_b64 v[228:231], v247 offset0:196 offset1:198
	ds_read2_b64 v[232:235], v243 offset0:136 offset1:138
	ds_read2_b64 v[236:239], v247 offset0:200 offset1:202
	ds_read2_b64 v[240:243], v243 offset0:140 offset1:142
	ds_read2_b64 v[244:247], v247 offset0:204 offset1:206
	v_max3_f32 v12, v14, v176, v177
	v_sub_f32_e32 v176, v12, v14
	v_mul_f32_e32 v176, 0x3e38aa3b, v176
	v_cmp_lt_f32_e32 vcc, s51, v176
	s_cbranch_vccnz .LBB0_584
	v_mov_b32_e32 v12, v14
	s_branch .LBB0_585
